# MLA mixer: one barrier per two key tiles (two pairs of LDS tile buffers), halves still staggered
# baseline (speedup 1.0000x reference)
.LBB0_766:
	s_lshl_b32 s1, s14, 5
	s_and_b32 s0, s14, 0xffffff00
	s_and_b32 s1, s1, 0xe0
	s_or_b32 s0, s1, s0
	s_bfe_u32 s1, s14, 0x50003
	s_or_b32 s2, s0, s1
	v_readlane_b32 s0, v254, 15
	v_readlane_b32 s1, v254, 16
	s_and_b64 s[0:1], s[0:1], exec
	s_cselect_b32 s2, s2, s14
	s_bfe_u32 s12, s2, 0x20003
	s_ashr_i32 s16, s2, 5
	v_mov_b32_e32 v0, v185
	s_mov_b64 s[4:5], s[40:41]
	s_mul_i32 s0, s12, 0xc0
	s_add_u32 s0, s4, s0
	s_addc_u32 s1, s5, 0
	s_add_u32 s0, s0, 0x16e00000
	s_addc_u32 s1, s1, 0
	s_lshl_b32 s3, s12, 7
	s_add_u32 s3, s4, s3
	s_addc_u32 s7, s5, 0
	s_add_u32 s6, s3, 0x18900000
	s_addc_u32 s7, s7, 0
	v_mbcnt_lo_u32_b32 v0, -1, v0
	s_add_u32 s8, s4, 0xba01300
	v_mbcnt_hi_u32_b32 v22, -1, v0
	s_addc_u32 s9, s5, 0
	s_lshl_b32 s2, s2, 8
	v_and_b32_e32 v23, 31, v22
	s_lshl_b32 s15, s16, 11
	s_and_b32 s2, s2, 0x700
	v_readlane_b32 s3, v255, 6
	s_or_b32 s2, s2, s15
	v_bfe_u32 v24, v22, 5, 1
	v_or_b32_e32 v0, s3, v23
	v_add_u32_e32 v176, s2, v0
	v_mov_b64_e32 v[0:1], s[0:1]
	s_movk_i32 s0, 0x300
	v_mad_i64_i32 v[0:1], s[0:1], v176, s0, v[0:1]
	v_lshlrev_b32_e32 v184, 4, v24
	v_lshl_add_u64 v[0:1], v[0:1], 0, v[184:185]
	global_load_dwordx4 v[96:99], v[0:1], off
	global_load_dwordx4 v[100:103], v[0:1], off offset:32
	global_load_dwordx4 v[104:107], v[0:1], off offset:64
	global_load_dwordx4 v[108:111], v[0:1], off offset:96
	global_load_dwordx4 v[112:115], v[0:1], off offset:128
	global_load_dwordx4 v[116:119], v[0:1], off offset:160
	v_readlane_b32 s0, v252, 16
	s_nop 1
	v_add_u32_e32 v8, s0, v22
	s_mov_b32 s0, 0x2aaaaaab
	v_mul_hi_i32 v0, v8, s0
	v_lshrrev_b32_e32 v1, 31, v0
	v_ashrrev_i32_e32 v0, 1, v0
	v_add_u32_e32 v194, v0, v1
	v_mul_lo_u32 v0, v194, 12
	v_sub_u32_e32 v25, v8, v0
	v_add_u32_e32 v2, s15, v194
	v_cmp_lt_i32_e64 s[0:1], 7, v25
	v_ashrrev_i32_e32 v3, 31, v2
	v_lshlrev_b32_e32 v12, 3, v25
	s_and_saveexec_b64 s[2:3], s[0:1]
	s_xor_b64 s[2:3], exec, s[2:3]
	v_mov_b64_e32 v[0:1], s[8:9]
	v_mad_i64_i32 v[0:1], s[10:11], v2, s33, v[0:1]
	v_mov_b32_e32 v13, v185
	v_lshl_add_u64 v[0:1], v[12:13], 1, v[0:1]
	v_lshl_add_u64 v[0:1], v[0:1], 0, s[28:29]
	s_or_saveexec_b64 s[2:3], s[2:3]
	v_ashrrev_i32_e32 v26, 31, v12
	s_xor_b64 exec, exec, s[2:3]
	v_lshlrev_b64 v[0:1], 9, v[2:3]
	v_lshl_add_u64 v[0:1], s[6:7], 0, v[0:1]
	v_mov_b32_e32 v13, v26
	v_lshl_add_u64 v[0:1], v[12:13], 1, v[0:1]
	s_or_b64 exec, exec, s[2:3]
	global_load_dwordx4 v[0:3], v[0:1], off
	v_bitop3_b16 v4, v8, s26, v251 bitop3:0xec
	s_mov_b32 s2, 0xaaab
	v_mul_u32_u24_sdwa v5, v4, s2 dst_sel:DWORD dst_unused:UNUSED_PAD src0_sel:WORD_0 src1_sel:DWORD
	v_lshrrev_b32_e32 v195, 19, v5
	v_mul_lo_u16_e32 v5, 12, v195
	v_sub_u16_e32 v27, v4, v5
	v_or_b32_e32 v6, s15, v195
	v_lshlrev_b32_e32 v4, 3, v27
	v_cmp_lt_u16_e64 s[2:3], 7, v27
	v_ashrrev_i32_e32 v7, 31, v6
	v_lshlrev_b32_e32 v14, 1, v4
	s_and_saveexec_b64 s[10:11], s[2:3]
	s_xor_b64 s[10:11], exec, s[10:11]
	v_mov_b64_e32 v[4:5], s[8:9]
	v_mad_i64_i32 v[4:5], s[18:19], v6, s33, v[4:5]
	v_mov_b32_e32 v15, v185
	v_lshl_add_u64 v[4:5], v[4:5], 0, v[14:15]
	v_lshl_add_u64 v[4:5], v[4:5], 0, s[28:29]
	s_andn2_saveexec_b64 s[10:11], s[10:11]
	v_lshlrev_b64 v[4:5], 9, v[6:7]
	v_lshl_add_u64 v[4:5], s[6:7], 0, v[4:5]
	v_mov_b32_e32 v15, v185
	v_lshl_add_u64 v[4:5], v[4:5], 0, v[14:15]
	s_or_b64 exec, exec, s[10:11]
	s_lshl_b32 s10, s12, 6
	s_lshl_b32 s60, s10, 1
	s_add_u32 s10, s4, s60
	v_ashrrev_i32_e32 v196, 3, v8
	s_addc_u32 s11, s5, 0
	v_add_u32_e32 v8, s15, v196
	s_add_u32 s10, s10, 0x19b00000
	v_ashrrev_i32_e32 v9, 31, v8
	s_addc_u32 s11, s11, 0
	v_and_b32_e32 v28, 7, v22
	v_lshlrev_b64 v[8:9], 9, v[8:9]
	v_lshl_add_u64 v[8:9], s[10:11], 0, v[8:9]
	v_lshlrev_b32_e32 v16, 4, v28
	v_mov_b32_e32 v17, v185
	v_lshl_add_u64 v[8:9], v[8:9], 0, v[16:17]
	global_load_dwordx4 v[4:7], v[4:5], off
	s_or_b32 s17, s15, 64
	global_load_dwordx4 v[8:11], v[8:9], off
	v_add_u32_e32 v20, s17, v194
	v_ashrrev_i32_e32 v21, 31, v20
	s_and_saveexec_b64 s[12:13], s[0:1]
	s_xor_b64 s[12:13], exec, s[12:13]
	v_mov_b64_e32 v[18:19], s[8:9]
	v_mad_i64_i32 v[18:19], s[18:19], v20, s33, v[18:19]
	v_mov_b32_e32 v13, v185
	v_lshl_add_u64 v[18:19], v[12:13], 1, v[18:19]
	v_lshl_add_u64 v[18:19], v[18:19], 0, s[28:29]
	s_andn2_saveexec_b64 s[12:13], s[12:13]
	v_lshlrev_b64 v[18:19], 9, v[20:21]
	v_lshl_add_u64 v[18:19], s[6:7], 0, v[18:19]
	v_mov_b32_e32 v13, v26
	v_lshl_add_u64 v[18:19], v[12:13], 1, v[18:19]
	s_or_b64 exec, exec, s[12:13]
	global_load_dwordx4 v[120:123], v[18:19], off
	v_or_b32_e32 v20, s17, v195
	v_ashrrev_i32_e32 v21, 31, v20
	s_and_saveexec_b64 s[12:13], s[2:3]
	s_xor_b64 s[12:13], exec, s[12:13]
	v_mov_b64_e32 v[18:19], s[8:9]
	v_mad_i64_i32 v[18:19], s[18:19], v20, s33, v[18:19]
	v_mov_b32_e32 v15, v185
	v_lshl_add_u64 v[18:19], v[18:19], 0, v[14:15]
	v_lshl_add_u64 v[18:19], v[18:19], 0, s[28:29]
	s_andn2_saveexec_b64 s[12:13], s[12:13]
	v_lshlrev_b64 v[18:19], 9, v[20:21]
	v_lshl_add_u64 v[18:19], s[6:7], 0, v[18:19]
	v_mov_b32_e32 v15, v185
	v_lshl_add_u64 v[18:19], v[18:19], 0, v[14:15]
	s_or_b64 exec, exec, s[12:13]
	global_load_dwordx4 v[124:127], v[18:19], off
	v_add_u32_e32 v18, s17, v196
	v_ashrrev_i32_e32 v19, 31, v18
	v_lshlrev_b32_e32 v13, 3, v28
	v_lshlrev_b64 v[18:19], 9, v[18:19]
	v_lshl_add_u64 v[18:19], s[10:11], 0, v[18:19]
	v_lshlrev_b32_e32 v20, 1, v13
	v_mov_b32_e32 v21, v185
	v_lshl_add_u64 v[18:19], v[18:19], 0, v[20:21]
	global_load_dwordx4 v[128:131], v[18:19], off
	v_mul_lo_u32 v13, v194, s81
	v_add_u32_e32 v13, 0, v13
	v_lshlrev_b32_e32 v15, 4, v25
	v_add_u32_e32 v198, v13, v15
	s_waitcnt vmcnt(5)
	ds_write_b128 v198, v[0:3]
	v_mad_u32_u24 v0, v195, s81, 0
	v_lshlrev_b32_e32 v1, 4, v27
	v_add_u32_e32 v199, v0, v1
	v_mul_lo_u32 v0, v196, s80
	v_add_u32_e32 v0, 0, v0
	v_add_u32_e32 v200, v0, v16
	v_bfe_u32 v0, v22, 2, 2
	v_lshl_or_b32 v0, v24, 2, v0
	s_waitcnt vmcnt(4)
	ds_write_b128 v199, v[4:7]
	s_waitcnt vmcnt(3)
	ds_write_b128 v200, v[8:11] offset:26624
	v_mad_u32_u24 v33, v0, s80, 0
	v_and_b32_e32 v0, 16, v22
	v_lshlrev_b32_e32 v1, 2, v23
	s_waitcnt lgkmcnt(0)
	s_barrier
	v_and_or_b32 v0, v1, 12, v0
	v_mov_b32_e32 v13, v185
	s_lshl_b32 s12, s16, 8
	v_mad_u32_u24 v32, v23, s81, 0
	v_lshlrev_b32_e32 v34, 1, v0
	v_lshl_add_u64 v[180:181], v[12:13], 1, s[8:9]
	v_mov_b32_e32 v13, v26
	v_mov_b32_e32 v15, v185
	v_mov_b32_e32 v203, 0
	v_ashrrev_i32_e32 v177, 31, v176
	v_lshlrev_b32_e32 v197, 3, v24
	s_add_i32 s12, s12, 0x8000
	v_lshl_add_u64 v[178:179], s[10:11], 0, v[20:21]
	v_lshl_add_u64 v[182:183], v[12:13], 1, s[6:7]
	v_lshl_add_u64 v[190:191], s[8:9], 0, v[14:15]
	v_lshl_add_u64 v[192:193], s[6:7], 0, v[14:15]
	s_mov_b32 s13, 0
	v_mov_b32_e32 v16, v185
	v_mov_b32_e32 v17, v185
	v_mov_b32_e32 v18, v185
	v_mov_b32_e32 v19, v185
	v_mov_b32_e32 v20, v185
	v_mov_b32_e32 v22, v185
	v_mov_b32_e32 v23, v185
	v_mov_b32_e32 v24, v185
	v_mov_b32_e32 v25, v185
	v_mov_b32_e32 v26, v185
	v_mov_b32_e32 v27, v185
	v_mov_b32_e32 v28, v185
	v_mov_b32_e32 v29, v185
	v_mov_b32_e32 v30, v185
	v_mov_b32_e32 v31, v185
	v_mov_b32_e32 v0, v185
	v_mov_b32_e32 v1, v185
	v_mov_b32_e32 v2, v185
	v_mov_b32_e32 v3, v185
	v_mov_b32_e32 v4, v185
	v_mov_b32_e32 v5, v185
	v_mov_b32_e32 v6, v185
	v_mov_b32_e32 v7, v185
	v_mov_b32_e32 v8, v185
	v_mov_b32_e32 v9, v185
	v_mov_b32_e32 v10, v185
	v_mov_b32_e32 v11, v185
	v_mov_b32_e32 v12, v185
	v_mov_b32_e32 v13, v185
	v_mov_b32_e32 v14, v185
	v_add_u32_e32 v184, v32, v184
	v_add_u32_e32 v201, v33, v34
	v_mov_b32_e32 v202, 0
	v_mov_b32_e32 v32, 0
	v_mov_b32_e32 v33, v203
	v_mov_b32_e32 v34, v203
	v_mov_b32_e32 v35, v203
	v_mov_b32_e32 v36, v203
	v_mov_b32_e32 v37, v203
	v_mov_b32_e32 v38, v203
	v_mov_b32_e32 v39, v203
	v_mov_b32_e32 v40, v203
	v_mov_b32_e32 v41, v203
	v_mov_b32_e32 v42, v203
	v_mov_b32_e32 v43, v203
	v_mov_b32_e32 v44, v203
	v_mov_b32_e32 v45, v203
	v_mov_b32_e32 v46, v203
	v_mov_b32_e32 v47, v203
	v_readlane_b32 s99, v255, 23
	s_waitcnt vmcnt(0)
	ds_write_b128 v198, v[120:123] offset:13312
	ds_write_b128 v199, v[124:127] offset:13312
	ds_write_b128 v200, v[128:131] offset:38912
	s_mov_b32 s13, 0
	s_add_i32 s16, s13, 2
	s_min_u32 s6, s16, 35
	s_cmp_lt_u32 s16, 32
	s_cselect_b32 s7, 0, 0xffffffe0
	s_cselect_b32 s8, s15, s12
	s_add_i32 s7, s7, s6
	s_lshl_b32 s6, s7, 6
	s_add_i32 s8, s6, s8
	v_add_u32_e32 v208, s8, v194
	v_ashrrev_i32_e32 v209, 31, v208
	s_and_saveexec_b64 s[6:7], s[0:1]
	s_xor_b64 s[6:7], exec, s[6:7]
	v_mad_i64_i32 v[206:207], s[10:11], v208, s33, v[180:181]
	v_lshl_add_u64 v[206:207], v[206:207], 0, s[28:29]
	s_andn2_saveexec_b64 s[6:7], s[6:7]
	v_lshlrev_b64 v[206:207], 9, v[208:209]
	v_lshl_add_u64 v[206:207], v[182:183], 0, v[206:207]
	s_or_b64 exec, exec, s[6:7]
	global_load_dwordx4 v[132:135], v[206:207], off
	v_or_b32_e32 v208, s8, v195
	v_ashrrev_i32_e32 v209, 31, v208
	s_and_saveexec_b64 s[6:7], s[2:3]
	s_xor_b64 s[6:7], exec, s[6:7]
	v_mad_i64_i32 v[206:207], s[10:11], v208, s33, v[190:191]
	v_lshl_add_u64 v[206:207], v[206:207], 0, s[28:29]
	s_andn2_saveexec_b64 s[6:7], s[6:7]
	v_lshlrev_b64 v[206:207], 9, v[208:209]
	v_lshl_add_u64 v[206:207], v[192:193], 0, v[206:207]
	s_or_b64 exec, exec, s[6:7]
	global_load_dwordx4 v[136:139], v[206:207], off
	v_add_u32_e32 v206, s8, v196
	v_ashrrev_i32_e32 v207, 31, v206
	v_lshlrev_b64 v[206:207], 9, v[206:207]
	v_lshl_add_u64 v[206:207], v[178:179], 0, v[206:207]
	global_load_dwordx4 v[140:143], v[206:207], off
	s_add_i32 s16, s13, 3
	s_min_u32 s6, s16, 35
	s_cmp_lt_u32 s16, 32
	s_cselect_b32 s7, 0, 0xffffffe0
	s_cselect_b32 s8, s15, s12
	s_add_i32 s7, s7, s6
	s_lshl_b32 s6, s7, 6
	s_add_i32 s8, s6, s8
	v_add_u32_e32 v208, s8, v194
	v_ashrrev_i32_e32 v209, 31, v208
	s_and_saveexec_b64 s[6:7], s[0:1]
	s_xor_b64 s[6:7], exec, s[6:7]
	v_mad_i64_i32 v[206:207], s[10:11], v208, s33, v[180:181]
	v_lshl_add_u64 v[206:207], v[206:207], 0, s[28:29]
	s_andn2_saveexec_b64 s[6:7], s[6:7]
	v_lshlrev_b64 v[206:207], 9, v[208:209]
	v_lshl_add_u64 v[206:207], v[182:183], 0, v[206:207]
	s_or_b64 exec, exec, s[6:7]
	global_load_dwordx4 v[120:123], v[206:207], off
	v_or_b32_e32 v208, s8, v195
	v_ashrrev_i32_e32 v209, 31, v208
	s_and_saveexec_b64 s[6:7], s[2:3]
	s_xor_b64 s[6:7], exec, s[6:7]
	v_mad_i64_i32 v[206:207], s[10:11], v208, s33, v[190:191]
	v_lshl_add_u64 v[206:207], v[206:207], 0, s[28:29]
	s_andn2_saveexec_b64 s[6:7], s[6:7]
	v_lshlrev_b64 v[206:207], 9, v[208:209]
	v_lshl_add_u64 v[206:207], v[192:193], 0, v[206:207]
	s_or_b64 exec, exec, s[6:7]
	global_load_dwordx4 v[124:127], v[206:207], off
	v_add_u32_e32 v206, s8, v196
	v_ashrrev_i32_e32 v207, 31, v206
	v_lshlrev_b64 v[206:207], 9, v[206:207]
	v_lshl_add_u64 v[206:207], v[178:179], 0, v[206:207]
	global_load_dwordx4 v[128:131], v[206:207], off
	s_waitcnt lgkmcnt(0)
	s_barrier
.LBB0_783:
	s_and_b32 s6, s13, 2
	s_mul_i32 s6, s6, 25600
	s_sub_i32 s7, 51200, s6
	v_add_u32_e32 v213, s6, v184
	v_add_u32_e32 v214, s6, v201
	v_add_u32_e32 v215, s7, v198
	v_add_u32_e32 v216, s7, v199
	v_add_u32_e32 v217, s7, v200
	ds_read_b128 v[48:51], v213 offset:0
	ds_read_b128 v[52:55], v213 offset:32
	ds_read_b128 v[56:59], v213 offset:64
	ds_read_b128 v[60:63], v213 offset:96
	ds_read_b128 v[64:67], v213 offset:128
	ds_read_b128 v[68:71], v213 offset:160
	ds_read_b128 v[72:75], v213 offset:6656
	ds_read_b128 v[76:79], v213 offset:6688
	ds_read_b128 v[80:83], v213 offset:6720
	ds_read_b128 v[84:87], v213 offset:6752
	ds_read_b128 v[88:91], v213 offset:6784
	ds_read_b128 v[92:95], v213 offset:6816
	s_waitcnt lgkmcnt(11)
	v_mfma_f32_32x32x16_bf16 v[144:159], v[48:51], v[96:99], v[32:47]
	s_waitcnt lgkmcnt(10)
	v_mfma_f32_32x32x16_bf16 v[144:159], v[52:55], v[100:103], v[144:159]
	s_waitcnt lgkmcnt(9)
	v_mfma_f32_32x32x16_bf16 v[144:159], v[56:59], v[104:107], v[144:159]
	s_waitcnt lgkmcnt(8)
	v_mfma_f32_32x32x16_bf16 v[144:159], v[60:63], v[108:111], v[144:159]
	s_waitcnt lgkmcnt(7)
	v_mfma_f32_32x32x16_bf16 v[144:159], v[64:67], v[112:115], v[144:159]
	s_waitcnt lgkmcnt(6)
	v_mfma_f32_32x32x16_bf16 v[144:159], v[68:71], v[116:119], v[144:159]
	s_waitcnt lgkmcnt(5)
	v_mfma_f32_32x32x16_bf16 v[160:175], v[72:75], v[96:99], v[32:47]
	s_waitcnt lgkmcnt(4)
	v_mfma_f32_32x32x16_bf16 v[160:175], v[76:79], v[100:103], v[160:175]
	s_waitcnt lgkmcnt(3)
	v_mfma_f32_32x32x16_bf16 v[160:175], v[80:83], v[104:107], v[160:175]
	s_waitcnt lgkmcnt(2)
	v_mfma_f32_32x32x16_bf16 v[160:175], v[84:87], v[108:111], v[160:175]
	s_waitcnt lgkmcnt(1)
	v_mfma_f32_32x32x16_bf16 v[160:175], v[88:91], v[112:115], v[160:175]
	s_waitcnt lgkmcnt(0)
	v_mfma_f32_32x32x16_bf16 v[160:175], v[92:95], v[116:119], v[160:175]
	ds_read_b64_tr_b16 v[48:49], v214 offset:26624
	ds_read_b64_tr_b16 v[50:51], v214 offset:28160
	ds_read_b64_tr_b16 v[52:53], v214 offset:26688
	ds_read_b64_tr_b16 v[54:55], v214 offset:28224
	ds_read_b64_tr_b16 v[56:57], v214 offset:29696
	ds_read_b64_tr_b16 v[58:59], v214 offset:31232
	ds_read_b64_tr_b16 v[60:61], v214 offset:29760
	ds_read_b64_tr_b16 v[62:63], v214 offset:31296
	ds_read_b64_tr_b16 v[64:65], v214 offset:32768
	ds_read_b64_tr_b16 v[66:67], v214 offset:34304
	ds_read_b64_tr_b16 v[68:69], v214 offset:32832
	ds_read_b64_tr_b16 v[70:71], v214 offset:34368
	ds_read_b64_tr_b16 v[72:73], v214 offset:35840
	ds_read_b64_tr_b16 v[74:75], v214 offset:37376
	ds_read_b64_tr_b16 v[76:77], v214 offset:35904
	ds_read_b64_tr_b16 v[78:79], v214 offset:37440
	v_exp_f32_e32 v144, v144
	v_exp_f32_e32 v145, v145
	v_exp_f32_e32 v146, v146
	v_exp_f32_e32 v147, v147
	v_exp_f32_e32 v148, v148
	v_exp_f32_e32 v149, v149
	v_exp_f32_e32 v150, v150
	v_exp_f32_e32 v151, v151
	v_add_f32_e32 v204, v144, v146
	v_add_f32_e32 v205, v145, v147
	v_add_f32_e32 v204, v204, v148
	v_add_f32_e32 v205, v205, v149
	v_add_f32_e32 v204, v204, v150
	v_add_f32_e32 v205, v205, v151
	v_cvt_pk_bf16_f32 v144, v144, v145
	v_cvt_pk_bf16_f32 v145, v146, v147
	v_cvt_pk_bf16_f32 v146, v148, v149
	v_cvt_pk_bf16_f32 v147, v150, v151
	v_exp_f32_e32 v152, v152
	v_exp_f32_e32 v153, v153
	s_waitcnt lgkmcnt(14)
	v_mfma_f32_32x32x16_bf16 v[16:31], v[48:51], v[144:147], v[16:31]
	v_exp_f32_e32 v154, v154
	v_exp_f32_e32 v155, v155
	v_exp_f32_e32 v156, v156
	s_waitcnt lgkmcnt(12)
	v_mfma_f32_32x32x16_bf16 v[0:15], v[52:55], v[144:147], v[0:15]
	v_exp_f32_e32 v157, v157
	v_exp_f32_e32 v158, v158
	v_exp_f32_e32 v159, v159
	v_add_f32_e32 v204, v204, v152
	v_add_f32_e32 v205, v205, v153
	v_add_f32_e32 v204, v204, v154
	v_add_f32_e32 v205, v205, v155
	v_add_f32_e32 v204, v204, v156
	v_add_f32_e32 v205, v205, v157
	v_add_f32_e32 v204, v204, v158
	v_add_f32_e32 v205, v205, v159
	v_cvt_pk_bf16_f32 v152, v152, v153
	v_cvt_pk_bf16_f32 v153, v154, v155
	v_cvt_pk_bf16_f32 v154, v156, v157
	v_cvt_pk_bf16_f32 v155, v158, v159
	v_exp_f32_e32 v160, v160
	v_exp_f32_e32 v161, v161
	s_waitcnt lgkmcnt(10)
	v_mfma_f32_32x32x16_bf16 v[16:31], v[56:59], v[152:155], v[16:31]
	v_exp_f32_e32 v162, v162
	v_exp_f32_e32 v163, v163
	v_exp_f32_e32 v164, v164
	s_waitcnt lgkmcnt(8)
	v_mfma_f32_32x32x16_bf16 v[0:15], v[60:63], v[152:155], v[0:15]
	v_exp_f32_e32 v165, v165
	v_exp_f32_e32 v166, v166
	v_exp_f32_e32 v167, v167
	v_add_f32_e32 v204, v204, v160
	v_add_f32_e32 v205, v205, v161
	v_add_f32_e32 v204, v204, v162
	v_add_f32_e32 v205, v205, v163
	v_add_f32_e32 v204, v204, v164
	v_add_f32_e32 v205, v205, v165
	v_add_f32_e32 v204, v204, v166
	v_add_f32_e32 v205, v205, v167
	v_cvt_pk_bf16_f32 v160, v160, v161
	v_cvt_pk_bf16_f32 v161, v162, v163
	v_cvt_pk_bf16_f32 v162, v164, v165
	v_cvt_pk_bf16_f32 v163, v166, v167
	v_exp_f32_e32 v168, v168
	v_exp_f32_e32 v169, v169
	s_waitcnt lgkmcnt(6)
	v_mfma_f32_32x32x16_bf16 v[16:31], v[64:67], v[160:163], v[16:31]
	v_exp_f32_e32 v170, v170
	v_exp_f32_e32 v171, v171
	v_exp_f32_e32 v172, v172
	s_waitcnt lgkmcnt(4)
	v_mfma_f32_32x32x16_bf16 v[0:15], v[68:71], v[160:163], v[0:15]
	v_exp_f32_e32 v173, v173
	v_exp_f32_e32 v174, v174
	v_exp_f32_e32 v175, v175
	v_add_f32_e32 v204, v204, v168
	v_add_f32_e32 v205, v205, v169
	v_add_f32_e32 v204, v204, v170
	v_add_f32_e32 v205, v205, v171
	v_add_f32_e32 v204, v204, v172
	v_add_f32_e32 v205, v205, v173
	v_add_f32_e32 v204, v204, v174
	v_add_f32_e32 v205, v205, v175
	v_cvt_pk_bf16_f32 v168, v168, v169
	v_cvt_pk_bf16_f32 v169, v170, v171
	v_cvt_pk_bf16_f32 v170, v172, v173
	v_cvt_pk_bf16_f32 v171, v174, v175
	s_nop 1
	s_waitcnt lgkmcnt(2)
	v_mfma_f32_32x32x16_bf16 v[16:31], v[72:75], v[168:171], v[16:31]
	s_waitcnt lgkmcnt(0)
	v_mfma_f32_32x32x16_bf16 v[0:15], v[76:79], v[168:171], v[0:15]
	s_cmp_gt_u32 s13, 33
	s_cbranch_scc1 .Lm1_skipwyA
	s_waitcnt vmcnt(5)
	ds_write_b128 v215, v[132:135]
	s_waitcnt vmcnt(4)
	ds_write_b128 v216, v[136:139]
	s_waitcnt vmcnt(3)
	ds_write_b128 v217, v[140:143] offset:26624
	s_add_i32 s16, s13, 4
	s_min_u32 s6, s16, 35
	s_cmp_lt_u32 s16, 32
	s_cselect_b32 s7, 0, 0xffffffe0
	s_cselect_b32 s8, s15, s12
	s_add_i32 s7, s7, s6
	s_lshl_b32 s6, s7, 6
	s_add_i32 s8, s6, s8
	v_add_u32_e32 v208, s8, v194
	v_ashrrev_i32_e32 v209, 31, v208
	s_and_saveexec_b64 s[6:7], s[0:1]
	s_xor_b64 s[6:7], exec, s[6:7]
	v_mad_i64_i32 v[206:207], s[10:11], v208, s33, v[180:181]
	v_lshl_add_u64 v[206:207], v[206:207], 0, s[28:29]
	s_andn2_saveexec_b64 s[6:7], s[6:7]
	v_lshlrev_b64 v[206:207], 9, v[208:209]
	v_lshl_add_u64 v[206:207], v[182:183], 0, v[206:207]
	s_or_b64 exec, exec, s[6:7]
	global_load_dwordx4 v[132:135], v[206:207], off
	v_or_b32_e32 v208, s8, v195
	v_ashrrev_i32_e32 v209, 31, v208
	s_and_saveexec_b64 s[6:7], s[2:3]
	s_xor_b64 s[6:7], exec, s[6:7]
	v_mad_i64_i32 v[206:207], s[10:11], v208, s33, v[190:191]
	v_lshl_add_u64 v[206:207], v[206:207], 0, s[28:29]
	s_andn2_saveexec_b64 s[6:7], s[6:7]
	v_lshlrev_b64 v[206:207], 9, v[208:209]
	v_lshl_add_u64 v[206:207], v[192:193], 0, v[206:207]
	s_or_b64 exec, exec, s[6:7]
	global_load_dwordx4 v[136:139], v[206:207], off
	v_add_u32_e32 v206, s8, v196
	v_ashrrev_i32_e32 v207, 31, v206
	v_lshlrev_b64 v[206:207], 9, v[206:207]
	v_lshl_add_u64 v[206:207], v[178:179], 0, v[206:207]
	global_load_dwordx4 v[140:143], v[206:207], off

.Lm1_noresA:
	ds_read_b128 v[48:51], v213 offset:13312
	ds_read_b128 v[52:55], v213 offset:13344
	ds_read_b128 v[56:59], v213 offset:13376
	ds_read_b128 v[60:63], v213 offset:13408
	ds_read_b128 v[64:67], v213 offset:13440
	ds_read_b128 v[68:71], v213 offset:13472
	ds_read_b128 v[72:75], v213 offset:19968
	ds_read_b128 v[76:79], v213 offset:20000
	ds_read_b128 v[80:83], v213 offset:20032
	ds_read_b128 v[84:87], v213 offset:20064
	ds_read_b128 v[88:91], v213 offset:20096
	ds_read_b128 v[92:95], v213 offset:20128
	s_waitcnt lgkmcnt(11)
	v_mfma_f32_32x32x16_bf16 v[144:159], v[48:51], v[96:99], v[32:47]
	s_waitcnt lgkmcnt(10)
	v_mfma_f32_32x32x16_bf16 v[144:159], v[52:55], v[100:103], v[144:159]
	s_waitcnt lgkmcnt(9)
	v_mfma_f32_32x32x16_bf16 v[144:159], v[56:59], v[104:107], v[144:159]
	s_waitcnt lgkmcnt(8)
	v_mfma_f32_32x32x16_bf16 v[144:159], v[60:63], v[108:111], v[144:159]
	s_waitcnt lgkmcnt(7)
	v_mfma_f32_32x32x16_bf16 v[144:159], v[64:67], v[112:115], v[144:159]
	s_waitcnt lgkmcnt(6)
	v_mfma_f32_32x32x16_bf16 v[144:159], v[68:71], v[116:119], v[144:159]
	s_waitcnt lgkmcnt(5)
	v_mfma_f32_32x32x16_bf16 v[160:175], v[72:75], v[96:99], v[32:47]
	s_waitcnt lgkmcnt(4)
	v_mfma_f32_32x32x16_bf16 v[160:175], v[76:79], v[100:103], v[160:175]
	s_waitcnt lgkmcnt(3)
	v_mfma_f32_32x32x16_bf16 v[160:175], v[80:83], v[104:107], v[160:175]
	s_waitcnt lgkmcnt(2)
	v_mfma_f32_32x32x16_bf16 v[160:175], v[84:87], v[108:111], v[160:175]
	s_waitcnt lgkmcnt(1)
	v_mfma_f32_32x32x16_bf16 v[160:175], v[88:91], v[112:115], v[160:175]
	s_waitcnt lgkmcnt(0)
	v_mfma_f32_32x32x16_bf16 v[160:175], v[92:95], v[116:119], v[160:175]
	ds_read_b64_tr_b16 v[48:49], v214 offset:38912
	ds_read_b64_tr_b16 v[50:51], v214 offset:40448
	ds_read_b64_tr_b16 v[52:53], v214 offset:38976
	ds_read_b64_tr_b16 v[54:55], v214 offset:40512
	ds_read_b64_tr_b16 v[56:57], v214 offset:41984
	ds_read_b64_tr_b16 v[58:59], v214 offset:43520
	ds_read_b64_tr_b16 v[60:61], v214 offset:42048
	ds_read_b64_tr_b16 v[62:63], v214 offset:43584
	ds_read_b64_tr_b16 v[64:65], v214 offset:45056
	ds_read_b64_tr_b16 v[66:67], v214 offset:46592
	ds_read_b64_tr_b16 v[68:69], v214 offset:45120
	ds_read_b64_tr_b16 v[70:71], v214 offset:46656
	ds_read_b64_tr_b16 v[72:73], v214 offset:48128
	ds_read_b64_tr_b16 v[74:75], v214 offset:49664
	ds_read_b64_tr_b16 v[76:77], v214 offset:48192
	ds_read_b64_tr_b16 v[78:79], v214 offset:49728
	s_cmp_eq_u32 s99, 0
	s_cbranch_scc0 .Lm1_xB
	s_cmp_gt_u32 s13, 33
	s_cbranch_scc1 .Lm1_skipwxB
	s_waitcnt vmcnt(5)
	ds_write_b128 v215, v[120:123] offset:13312
	s_waitcnt vmcnt(4)
	ds_write_b128 v216, v[124:127] offset:13312
	s_waitcnt vmcnt(3)
	ds_write_b128 v217, v[128:131] offset:38912
	s_add_i32 s16, s13, 5
	s_min_u32 s6, s16, 35
	s_cmp_lt_u32 s16, 32
	s_cselect_b32 s7, 0, 0xffffffe0
	s_cselect_b32 s8, s15, s12
	s_add_i32 s7, s7, s6
	s_lshl_b32 s6, s7, 6
	s_add_i32 s8, s6, s8
	v_add_u32_e32 v208, s8, v194
	v_ashrrev_i32_e32 v209, 31, v208
	s_and_saveexec_b64 s[6:7], s[0:1]
	s_xor_b64 s[6:7], exec, s[6:7]
	v_mad_i64_i32 v[206:207], s[10:11], v208, s33, v[180:181]
	v_lshl_add_u64 v[206:207], v[206:207], 0, s[28:29]
	s_andn2_saveexec_b64 s[6:7], s[6:7]
	v_lshlrev_b64 v[206:207], 9, v[208:209]
	v_lshl_add_u64 v[206:207], v[182:183], 0, v[206:207]
	s_or_b64 exec, exec, s[6:7]
	global_load_dwordx4 v[120:123], v[206:207], off
	v_or_b32_e32 v208, s8, v195
	v_ashrrev_i32_e32 v209, 31, v208
	s_and_saveexec_b64 s[6:7], s[2:3]
	s_xor_b64 s[6:7], exec, s[6:7]
	v_mad_i64_i32 v[206:207], s[10:11], v208, s33, v[190:191]
	v_lshl_add_u64 v[206:207], v[206:207], 0, s[28:29]
	s_andn2_saveexec_b64 s[6:7], s[6:7]
	v_lshlrev_b64 v[206:207], 9, v[208:209]
	v_lshl_add_u64 v[206:207], v[192:193], 0, v[206:207]
	s_or_b64 exec, exec, s[6:7]
	global_load_dwordx4 v[124:127], v[206:207], off
	v_add_u32_e32 v206, s8, v196
	v_ashrrev_i32_e32 v207, 31, v206
	v_lshlrev_b64 v[206:207], 9, v[206:207]
	v_lshl_add_u64 v[206:207], v[178:179], 0, v[206:207]
	global_load_dwordx4 v[128:131], v[206:207], off

.Lm1_xB:
	v_exp_f32_e32 v144, v144
	v_exp_f32_e32 v145, v145
	v_exp_f32_e32 v146, v146
	v_exp_f32_e32 v147, v147
	v_exp_f32_e32 v148, v148
	v_exp_f32_e32 v149, v149
	v_exp_f32_e32 v150, v150
	v_exp_f32_e32 v151, v151
	v_add_f32_e32 v204, v144, v146
	v_add_f32_e32 v205, v145, v147
	v_add_f32_e32 v204, v204, v148
	v_add_f32_e32 v205, v205, v149
	v_add_f32_e32 v204, v204, v150
	v_add_f32_e32 v205, v205, v151
	v_cvt_pk_bf16_f32 v144, v144, v145
	v_cvt_pk_bf16_f32 v145, v146, v147
	v_cvt_pk_bf16_f32 v146, v148, v149
	v_cvt_pk_bf16_f32 v147, v150, v151
	v_exp_f32_e32 v152, v152
	v_exp_f32_e32 v153, v153
	s_waitcnt lgkmcnt(14)
	v_mfma_f32_32x32x16_bf16 v[16:31], v[48:51], v[144:147], v[16:31]
	v_exp_f32_e32 v154, v154
	v_exp_f32_e32 v155, v155
	v_exp_f32_e32 v156, v156
	s_waitcnt lgkmcnt(12)
	v_mfma_f32_32x32x16_bf16 v[0:15], v[52:55], v[144:147], v[0:15]
	v_exp_f32_e32 v157, v157
	v_exp_f32_e32 v158, v158
	v_exp_f32_e32 v159, v159
	v_add_f32_e32 v204, v204, v152
	v_add_f32_e32 v205, v205, v153
	v_add_f32_e32 v204, v204, v154
	v_add_f32_e32 v205, v205, v155
	v_add_f32_e32 v204, v204, v156
	v_add_f32_e32 v205, v205, v157
	v_add_f32_e32 v204, v204, v158
	v_add_f32_e32 v205, v205, v159
	v_cvt_pk_bf16_f32 v152, v152, v153
	v_cvt_pk_bf16_f32 v153, v154, v155
	v_cvt_pk_bf16_f32 v154, v156, v157
	v_cvt_pk_bf16_f32 v155, v158, v159
	v_exp_f32_e32 v160, v160
	v_exp_f32_e32 v161, v161
	s_waitcnt lgkmcnt(10)
	v_mfma_f32_32x32x16_bf16 v[16:31], v[56:59], v[152:155], v[16:31]
	v_exp_f32_e32 v162, v162
	v_exp_f32_e32 v163, v163
	v_exp_f32_e32 v164, v164
	s_waitcnt lgkmcnt(8)
	v_mfma_f32_32x32x16_bf16 v[0:15], v[60:63], v[152:155], v[0:15]
	v_exp_f32_e32 v165, v165
	v_exp_f32_e32 v166, v166
	v_exp_f32_e32 v167, v167
	v_add_f32_e32 v204, v204, v160
	v_add_f32_e32 v205, v205, v161
	v_add_f32_e32 v204, v204, v162
	v_add_f32_e32 v205, v205, v163
	v_add_f32_e32 v204, v204, v164
	v_add_f32_e32 v205, v205, v165
	v_add_f32_e32 v204, v204, v166
	v_add_f32_e32 v205, v205, v167
	v_cvt_pk_bf16_f32 v160, v160, v161
	v_cvt_pk_bf16_f32 v161, v162, v163
	v_cvt_pk_bf16_f32 v162, v164, v165
	v_cvt_pk_bf16_f32 v163, v166, v167
	v_exp_f32_e32 v168, v168
	v_exp_f32_e32 v169, v169
	s_waitcnt lgkmcnt(6)
	v_mfma_f32_32x32x16_bf16 v[16:31], v[64:67], v[160:163], v[16:31]
	v_exp_f32_e32 v170, v170
	v_exp_f32_e32 v171, v171
	v_exp_f32_e32 v172, v172
	s_waitcnt lgkmcnt(4)
	v_mfma_f32_32x32x16_bf16 v[0:15], v[68:71], v[160:163], v[0:15]
	v_exp_f32_e32 v173, v173
	v_exp_f32_e32 v174, v174
	v_exp_f32_e32 v175, v175
	v_add_f32_e32 v204, v204, v168
	v_add_f32_e32 v205, v205, v169
	v_add_f32_e32 v204, v204, v170
	v_add_f32_e32 v205, v205, v171
	v_add_f32_e32 v204, v204, v172
	v_add_f32_e32 v205, v205, v173
	v_add_f32_e32 v204, v204, v174
	v_add_f32_e32 v205, v205, v175
	v_cvt_pk_bf16_f32 v168, v168, v169
	v_cvt_pk_bf16_f32 v169, v170, v171
	v_cvt_pk_bf16_f32 v170, v172, v173
	v_cvt_pk_bf16_f32 v171, v174, v175
	s_nop 1
	s_waitcnt lgkmcnt(2)
	v_mfma_f32_32x32x16_bf16 v[16:31], v[72:75], v[168:171], v[16:31]
	s_waitcnt lgkmcnt(0)
	v_mfma_f32_32x32x16_bf16 v[0:15], v[76:79], v[168:171], v[0:15]
	s_cmp_eq_u32 s99, 0
	s_cbranch_scc1 .Lm1_yB
	s_cmp_gt_u32 s13, 33
	s_cbranch_scc1 .Lm1_skipwyB
	s_waitcnt vmcnt(5)
	ds_write_b128 v215, v[120:123] offset:13312
	s_waitcnt vmcnt(4)
	ds_write_b128 v216, v[124:127] offset:13312
	s_waitcnt vmcnt(3)
	ds_write_b128 v217, v[128:131] offset:38912
	s_add_i32 s16, s13, 5
	s_min_u32 s6, s16, 35
	s_cmp_lt_u32 s16, 32
	s_cselect_b32 s7, 0, 0xffffffe0
	s_cselect_b32 s8, s15, s12
	s_add_i32 s7, s7, s6
	s_lshl_b32 s6, s7, 6
	s_add_i32 s8, s6, s8
	v_add_u32_e32 v208, s8, v194
	v_ashrrev_i32_e32 v209, 31, v208
	s_and_saveexec_b64 s[6:7], s[0:1]
	s_xor_b64 s[6:7], exec, s[6:7]
	v_mad_i64_i32 v[206:207], s[10:11], v208, s33, v[180:181]
	v_lshl_add_u64 v[206:207], v[206:207], 0, s[28:29]
	s_andn2_saveexec_b64 s[6:7], s[6:7]
	v_lshlrev_b64 v[206:207], 9, v[208:209]
	v_lshl_add_u64 v[206:207], v[182:183], 0, v[206:207]
	s_or_b64 exec, exec, s[6:7]
	global_load_dwordx4 v[120:123], v[206:207], off
	v_or_b32_e32 v208, s8, v195
	v_ashrrev_i32_e32 v209, 31, v208
	s_and_saveexec_b64 s[6:7], s[2:3]
	s_xor_b64 s[6:7], exec, s[6:7]
	v_mad_i64_i32 v[206:207], s[10:11], v208, s33, v[190:191]
	v_lshl_add_u64 v[206:207], v[206:207], 0, s[28:29]
	s_andn2_saveexec_b64 s[6:7], s[6:7]
	v_lshlrev_b64 v[206:207], 9, v[208:209]
	v_lshl_add_u64 v[206:207], v[192:193], 0, v[206:207]
	s_or_b64 exec, exec, s[6:7]
	global_load_dwordx4 v[124:127], v[206:207], off
	v_add_u32_e32 v206, s8, v196
	v_ashrrev_i32_e32 v207, 31, v206
	v_lshlrev_b64 v[206:207], 9, v[206:207]
	v_lshl_add_u64 v[206:207], v[178:179], 0, v[206:207]
	global_load_dwordx4 v[128:131], v[206:207], off
